# code layout: 3 no-op dwords in front of the residual GEMM K-loop head (compensated after the loop); no functional change
# speedup vs baseline: 1.0026x; 1.0026x over previous
.LBB0_636:
	s_add_u32 s22, s22, 0x80
	s_addc_u32 s23, s23, 0
	s_add_u32 s45, s24, 0x100
	v_mov_b32_e32 v2, 0
	s_addc_u32 s46, s25, 0
	s_mov_b32 s24, 0
	v_mov_b32_e32 v3, v2
	v_mov_b32_e32 v4, v2
	v_mov_b32_e32 v5, v2
	v_mov_b32_e32 v6, v2
	v_mov_b32_e32 v7, v2
	v_mov_b32_e32 v8, v2
	v_mov_b32_e32 v9, v2
	v_mov_b32_e32 v22, v2
	v_mov_b32_e32 v23, v2
	v_mov_b32_e32 v24, v2
	v_mov_b32_e32 v25, v2
	v_mov_b32_e32 v26, v2
	v_mov_b32_e32 v27, v2
	v_mov_b32_e32 v28, v2
	v_mov_b32_e32 v29, v2
	v_mov_b32_e32 v38, v2
	v_mov_b32_e32 v39, v2
	v_mov_b32_e32 v40, v2
	v_mov_b32_e32 v41, v2
	v_mov_b32_e32 v42, v2
	v_mov_b32_e32 v43, v2
	v_mov_b32_e32 v44, v2
	v_mov_b32_e32 v45, v2
	v_mov_b32_e32 v54, v2
	v_mov_b32_e32 v55, v2
	v_mov_b32_e32 v56, v2
	v_mov_b32_e32 v57, v2
	v_mov_b32_e32 v58, v2
	v_mov_b32_e32 v59, v2
	v_mov_b32_e32 v60, v2
	v_mov_b32_e32 v61, v2
	v_mov_b32_e32 v10, v2
	v_mov_b32_e32 v11, v2
	v_mov_b32_e32 v12, v2
	v_mov_b32_e32 v13, v2
	v_mov_b32_e32 v18, v2
	v_mov_b32_e32 v19, v2
	v_mov_b32_e32 v20, v2
	v_mov_b32_e32 v21, v2
	v_mov_b32_e32 v30, v2
	v_mov_b32_e32 v31, v2
	v_mov_b32_e32 v32, v2
	v_mov_b32_e32 v33, v2
	v_mov_b32_e32 v34, v2
	v_mov_b32_e32 v35, v2
	v_mov_b32_e32 v36, v2
	v_mov_b32_e32 v37, v2
	v_mov_b32_e32 v46, v2
	v_mov_b32_e32 v47, v2
	v_mov_b32_e32 v48, v2
	v_mov_b32_e32 v49, v2
	v_mov_b32_e32 v50, v2
	v_mov_b32_e32 v51, v2
	v_mov_b32_e32 v52, v2
	v_mov_b32_e32 v53, v2
	v_mov_b32_e32 v62, v2
	v_mov_b32_e32 v63, v2
	v_mov_b32_e32 v64, v2
	v_mov_b32_e32 v65, v2
	v_mov_b32_e32 v66, v2
	v_mov_b32_e32 v67, v2
	v_mov_b32_e32 v68, v2
	v_mov_b32_e32 v69, v2
	v_mov_b32_e32 v70, v2
	v_mov_b32_e32 v71, v2
	v_mov_b32_e32 v72, v2
	v_mov_b32_e32 v73, v2
	v_mov_b32_e32 v74, v2
	v_mov_b32_e32 v75, v2
	v_mov_b32_e32 v76, v2
	v_mov_b32_e32 v77, v2
	v_mov_b32_e32 v86, v2
	v_mov_b32_e32 v87, v2
	v_mov_b32_e32 v88, v2
	v_mov_b32_e32 v89, v2
	v_mov_b32_e32 v90, v2
	v_mov_b32_e32 v91, v2
	v_mov_b32_e32 v92, v2
	v_mov_b32_e32 v93, v2
	v_mov_b32_e32 v102, v2
	v_mov_b32_e32 v103, v2
	v_mov_b32_e32 v104, v2
	v_mov_b32_e32 v105, v2
	v_mov_b32_e32 v106, v2
	v_mov_b32_e32 v107, v2
	v_mov_b32_e32 v108, v2
	v_mov_b32_e32 v109, v2
	v_mov_b32_e32 v118, v2
	v_mov_b32_e32 v119, v2
	v_mov_b32_e32 v120, v2
	v_mov_b32_e32 v121, v2
	v_mov_b32_e32 v122, v2
	v_mov_b32_e32 v123, v2
	v_mov_b32_e32 v124, v2
	v_mov_b32_e32 v125, v2
	v_mov_b32_e32 v78, v2
	v_mov_b32_e32 v79, v2
	v_mov_b32_e32 v80, v2
	v_mov_b32_e32 v81, v2
	v_mov_b32_e32 v82, v2
	v_mov_b32_e32 v83, v2
	v_mov_b32_e32 v84, v2
	v_mov_b32_e32 v85, v2
	v_mov_b32_e32 v94, v2
	v_mov_b32_e32 v95, v2
	v_mov_b32_e32 v96, v2
	v_mov_b32_e32 v97, v2
	v_mov_b32_e32 v98, v2
	v_mov_b32_e32 v99, v2
	v_mov_b32_e32 v100, v2
	v_mov_b32_e32 v101, v2
	v_mov_b32_e32 v110, v2
	v_mov_b32_e32 v111, v2
	v_mov_b32_e32 v112, v2
	v_mov_b32_e32 v113, v2
	v_mov_b32_e32 v114, v2
	v_mov_b32_e32 v115, v2
	v_mov_b32_e32 v116, v2
	v_mov_b32_e32 v117, v2
	v_mov_b32_e32 v126, v2
	v_mov_b32_e32 v127, v2
	v_mov_b32_e32 v128, v2
	v_mov_b32_e32 v129, v2
	v_mov_b32_e32 v130, v2
	v_mov_b32_e32 v131, v2
	v_mov_b32_e32 v132, v2
	v_mov_b32_e32 v133, v2
	s_nop 0
	s_nop 0
	s_nop 0
.LBB0_637:
	s_add_i32 s47, s24, 2
	s_add_u32 s48, s22, 0x80
	s_addc_u32 s25, s23, 0
	s_add_i32 s50, 0, 0x10000
	s_cmp_eq_u32 s40, s24
	s_cselect_b32 s25, s7, s25
	s_cselect_b32 s24, s6, s48
	v_add_u32_e32 v135, s50, v249
	s_cselect_b32 s49, s21, s46
	s_cselect_b32 s48, s20, s45
	s_add_i32 s51, 0, 0x14000
	ds_read_b128 v[142:145], v135
	ds_read_b128 v[146:149], v135 offset:1024
	ds_read_b128 v[150:153], v135 offset:2048
	ds_read_b128 v[154:157], v135 offset:3072
	v_add_u32_e32 v135, s51, v249
	ds_read_b128 v[158:161], v135
	ds_read_b128 v[162:165], v135 offset:1024
	ds_read_b128 v[166:169], v135 offset:2048
	ds_read_b128 v[170:173], v135 offset:3072
	v_lshl_add_u64 v[174:175], s[22:23], 0, v[138:139]
	s_add_i32 m0, s31, 0xc000
	ds_read_b128 v[182:185], v251
	ds_read_b128 v[186:189], v251 offset:1024
	ds_read_b128 v[190:193], v251 offset:2048
	ds_read_b128 v[194:197], v251 offset:3072
	ds_read_b128 v[198:201], v251 offset:4096
	ds_read_b128 v[202:205], v251 offset:5120
	ds_read_b128 v[206:209], v251 offset:6144
	ds_read_b128 v[210:213], v251 offset:7168
	global_load_lds_dwordx4 v[174:175], off
	v_lshl_add_u64 v[174:175], s[22:23], 0, v[140:141]
	s_add_i32 m0, s31, 0xe000
	s_nop 0
	global_load_lds_dwordx4 v[174:175], off
	s_waitcnt vmcnt(8)
	s_waitcnt lgkmcnt(0)
	s_barrier
	s_setprio 1
	s_waitcnt lgkmcnt(0)
	v_mfma_f32_16x16x32_bf16 v[130:133], v[142:145], v[182:185], v[130:133]
	v_mfma_f32_16x16x32_bf16 v[130:133], v[146:149], v[186:189], v[130:133]
	v_mfma_f32_16x16x32_bf16 v[126:129], v[150:153], v[182:185], v[126:129]
	v_mfma_f32_16x16x32_bf16 v[126:129], v[154:157], v[186:189], v[126:129]
	v_mfma_f32_16x16x32_bf16 v[114:117], v[142:145], v[190:193], v[114:117]
	v_mfma_f32_16x16x32_bf16 v[114:117], v[146:149], v[194:197], v[114:117]
	v_mfma_f32_16x16x32_bf16 v[110:113], v[150:153], v[190:193], v[110:113]
	v_mfma_f32_16x16x32_bf16 v[110:113], v[154:157], v[194:197], v[110:113]
	v_mfma_f32_16x16x32_bf16 v[98:101], v[142:145], v[198:201], v[98:101]
	v_mfma_f32_16x16x32_bf16 v[98:101], v[146:149], v[202:205], v[98:101]
	v_mfma_f32_16x16x32_bf16 v[94:97], v[150:153], v[198:201], v[94:97]
	v_mfma_f32_16x16x32_bf16 v[94:97], v[154:157], v[202:205], v[94:97]
	v_mfma_f32_16x16x32_bf16 v[82:85], v[142:145], v[206:209], v[82:85]
	v_mfma_f32_16x16x32_bf16 v[82:85], v[146:149], v[210:213], v[82:85]
	v_mfma_f32_16x16x32_bf16 v[78:81], v[150:153], v[206:209], v[78:81]
	v_mfma_f32_16x16x32_bf16 v[78:81], v[154:157], v[210:213], v[78:81]
	s_setprio 0
	s_setprio 1
	v_mfma_f32_16x16x32_bf16 v[122:125], v[158:161], v[182:185], v[122:125]
	v_mfma_f32_16x16x32_bf16 v[122:125], v[162:165], v[186:189], v[122:125]
	v_mfma_f32_16x16x32_bf16 v[118:121], v[166:169], v[182:185], v[118:121]
	v_mfma_f32_16x16x32_bf16 v[118:121], v[170:173], v[186:189], v[118:121]
	v_mfma_f32_16x16x32_bf16 v[106:109], v[158:161], v[190:193], v[106:109]
	v_mfma_f32_16x16x32_bf16 v[106:109], v[162:165], v[194:197], v[106:109]
	v_mfma_f32_16x16x32_bf16 v[102:105], v[166:169], v[190:193], v[102:105]
	v_mfma_f32_16x16x32_bf16 v[102:105], v[170:173], v[194:197], v[102:105]
	v_mfma_f32_16x16x32_bf16 v[90:93], v[158:161], v[198:201], v[90:93]
	v_mfma_f32_16x16x32_bf16 v[90:93], v[162:165], v[202:205], v[90:93]
	v_mfma_f32_16x16x32_bf16 v[86:89], v[166:169], v[198:201], v[86:89]
	v_mfma_f32_16x16x32_bf16 v[86:89], v[170:173], v[202:205], v[86:89]
	v_mfma_f32_16x16x32_bf16 v[74:77], v[158:161], v[206:209], v[74:77]
	v_mfma_f32_16x16x32_bf16 v[74:77], v[162:165], v[210:213], v[74:77]
	v_mfma_f32_16x16x32_bf16 v[70:73], v[166:169], v[206:209], v[70:73]
	v_mfma_f32_16x16x32_bf16 v[70:73], v[170:173], v[210:213], v[70:73]
	s_setprio 0
	s_barrier
	s_add_i32 s50, s50, s30
	v_lshl_add_u64 v[174:175], s[48:49], 0, v[0:1]
	s_mov_b32 m0, s50
	ds_read_b128 v[182:185], v251 offset:16384
	ds_read_b128 v[186:189], v251 offset:17408
	ds_read_b128 v[190:193], v251 offset:18432
	ds_read_b128 v[194:197], v251 offset:19456
	ds_read_b128 v[198:201], v251 offset:20480
	ds_read_b128 v[202:205], v251 offset:21504
	ds_read_b128 v[206:209], v251 offset:22528
	ds_read_b128 v[210:213], v251 offset:23552
	global_load_lds_dwordx4 v[174:175], off
	s_add_i32 m0, s50, 0x2000
	v_lshl_add_u64 v[214:215], s[48:49], 0, v[14:15]
	s_add_u32 s48, s48, s10
	s_addc_u32 s49, s49, 0
	s_add_i32 s50, s51, s30
	global_load_lds_dwordx4 v[214:215], off
	v_lshl_add_u64 v[216:217], s[48:49], 0, v[0:1]
	s_mov_b32 m0, s50
	v_lshl_add_u64 v[218:219], s[48:49], 0, v[14:15]
	global_load_lds_dwordx4 v[216:217], off
	s_add_i32 m0, s50, 0x2000
	v_lshl_add_u64 v[220:221], s[24:25], 0, v[0:1]
	global_load_lds_dwordx4 v[218:219], off
	s_mov_b32 m0, s31
	v_lshl_add_u64 v[222:223], s[24:25], 0, v[14:15]
	global_load_lds_dwordx4 v[220:221], off
	s_mov_b32 m0, s34
	s_nop 0
	global_load_lds_dwordx4 v[222:223], off
	s_waitcnt vmcnt(8)
	s_waitcnt lgkmcnt(0)
	s_barrier
	s_setprio 1
	s_waitcnt lgkmcnt(0)
	v_mfma_f32_16x16x32_bf16 v[66:69], v[142:145], v[182:185], v[66:69]
	v_mfma_f32_16x16x32_bf16 v[66:69], v[146:149], v[186:189], v[66:69]
	v_mfma_f32_16x16x32_bf16 v[62:65], v[150:153], v[182:185], v[62:65]
	v_mfma_f32_16x16x32_bf16 v[62:65], v[154:157], v[186:189], v[62:65]
	v_mfma_f32_16x16x32_bf16 v[50:53], v[142:145], v[190:193], v[50:53]
	v_mfma_f32_16x16x32_bf16 v[50:53], v[146:149], v[194:197], v[50:53]
	v_mfma_f32_16x16x32_bf16 v[46:49], v[150:153], v[190:193], v[46:49]
	v_mfma_f32_16x16x32_bf16 v[46:49], v[154:157], v[194:197], v[46:49]
	v_mfma_f32_16x16x32_bf16 v[34:37], v[142:145], v[198:201], v[34:37]
	v_mfma_f32_16x16x32_bf16 v[34:37], v[146:149], v[202:205], v[34:37]
	v_mfma_f32_16x16x32_bf16 v[30:33], v[150:153], v[198:201], v[30:33]
	v_mfma_f32_16x16x32_bf16 v[30:33], v[154:157], v[202:205], v[30:33]
	v_mfma_f32_16x16x32_bf16 v[18:21], v[142:145], v[206:209], v[18:21]
	v_mfma_f32_16x16x32_bf16 v[18:21], v[146:149], v[210:213], v[18:21]
	v_mfma_f32_16x16x32_bf16 v[10:13], v[150:153], v[206:209], v[10:13]
	v_mfma_f32_16x16x32_bf16 v[10:13], v[154:157], v[210:213], v[10:13]
	s_setprio 0
	s_setprio 1
	v_mfma_f32_16x16x32_bf16 v[58:61], v[158:161], v[182:185], v[58:61]
	v_mfma_f32_16x16x32_bf16 v[58:61], v[162:165], v[186:189], v[58:61]
	v_mfma_f32_16x16x32_bf16 v[54:57], v[166:169], v[182:185], v[54:57]
	v_mfma_f32_16x16x32_bf16 v[54:57], v[170:173], v[186:189], v[54:57]
	v_mfma_f32_16x16x32_bf16 v[42:45], v[158:161], v[190:193], v[42:45]
	v_mfma_f32_16x16x32_bf16 v[42:45], v[162:165], v[194:197], v[42:45]
	v_mfma_f32_16x16x32_bf16 v[38:41], v[166:169], v[190:193], v[38:41]
	v_mfma_f32_16x16x32_bf16 v[38:41], v[170:173], v[194:197], v[38:41]
	v_mfma_f32_16x16x32_bf16 v[26:29], v[158:161], v[198:201], v[26:29]
	v_mfma_f32_16x16x32_bf16 v[26:29], v[162:165], v[202:205], v[26:29]
	v_mfma_f32_16x16x32_bf16 v[22:25], v[166:169], v[198:201], v[22:25]
	v_mfma_f32_16x16x32_bf16 v[22:25], v[170:173], v[202:205], v[22:25]
	v_mfma_f32_16x16x32_bf16 v[6:9], v[158:161], v[206:209], v[6:9]
	v_mfma_f32_16x16x32_bf16 v[6:9], v[162:165], v[210:213], v[6:9]
	v_mfma_f32_16x16x32_bf16 v[2:5], v[166:169], v[206:209], v[2:5]
	v_mfma_f32_16x16x32_bf16 v[2:5], v[170:173], v[210:213], v[2:5]
	s_setprio 0
	s_barrier
	s_add_i32 s48, 0, 0x18000
	v_add_u32_e32 v135, s48, v249
	s_add_i32 s49, 0, 0x1c000
	ds_read_b128 v[142:145], v135
	ds_read_b128 v[146:149], v135 offset:1024
	ds_read_b128 v[150:153], v135 offset:2048
	ds_read_b128 v[154:157], v135 offset:3072
	v_add_u32_e32 v135, s49, v249
	ds_read_b128 v[158:161], v135
	ds_read_b128 v[162:165], v135 offset:1024
	ds_read_b128 v[166:169], v135 offset:2048
	ds_read_b128 v[170:173], v135 offset:3072
	s_add_u32 s24, s24, s10
	s_addc_u32 s25, s25, 0
	s_mov_b32 m0, s35
	v_lshl_add_u64 v[224:225], s[24:25], 0, v[0:1]
	ds_read_b128 v[182:185], v251 offset:32768
	ds_read_b128 v[186:189], v251 offset:33792
	ds_read_b128 v[190:193], v251 offset:34816
	ds_read_b128 v[194:197], v251 offset:35840
	ds_read_b128 v[198:201], v251 offset:36864
	ds_read_b128 v[202:205], v251 offset:37888
	ds_read_b128 v[206:209], v251 offset:38912
	ds_read_b128 v[210:213], v251 offset:39936
	global_load_lds_dwordx4 v[224:225], off
	v_lshl_add_u64 v[224:225], s[24:25], 0, v[14:15]
	s_mov_b32 m0, s36
	s_nop 0
	global_load_lds_dwordx4 v[224:225], off
	s_waitcnt vmcnt(8)
	s_waitcnt lgkmcnt(0)
	s_barrier
	s_setprio 1
	s_waitcnt lgkmcnt(0)
	v_mfma_f32_16x16x32_bf16 v[130:133], v[142:145], v[182:185], v[130:133]
	v_mfma_f32_16x16x32_bf16 v[130:133], v[146:149], v[186:189], v[130:133]
	v_mfma_f32_16x16x32_bf16 v[126:129], v[150:153], v[182:185], v[126:129]
	v_mfma_f32_16x16x32_bf16 v[126:129], v[154:157], v[186:189], v[126:129]
	v_mfma_f32_16x16x32_bf16 v[114:117], v[142:145], v[190:193], v[114:117]
	v_mfma_f32_16x16x32_bf16 v[114:117], v[146:149], v[194:197], v[114:117]
	v_mfma_f32_16x16x32_bf16 v[110:113], v[150:153], v[190:193], v[110:113]
	v_mfma_f32_16x16x32_bf16 v[110:113], v[154:157], v[194:197], v[110:113]
	v_mfma_f32_16x16x32_bf16 v[98:101], v[142:145], v[198:201], v[98:101]
	v_mfma_f32_16x16x32_bf16 v[98:101], v[146:149], v[202:205], v[98:101]
	v_mfma_f32_16x16x32_bf16 v[94:97], v[150:153], v[198:201], v[94:97]
	v_mfma_f32_16x16x32_bf16 v[94:97], v[154:157], v[202:205], v[94:97]
	v_mfma_f32_16x16x32_bf16 v[82:85], v[142:145], v[206:209], v[82:85]
	v_mfma_f32_16x16x32_bf16 v[82:85], v[146:149], v[210:213], v[82:85]
	v_mfma_f32_16x16x32_bf16 v[78:81], v[150:153], v[206:209], v[78:81]
	v_mfma_f32_16x16x32_bf16 v[78:81], v[154:157], v[210:213], v[78:81]
	s_setprio 0
	s_setprio 1
	v_mfma_f32_16x16x32_bf16 v[122:125], v[158:161], v[182:185], v[122:125]
	v_mfma_f32_16x16x32_bf16 v[122:125], v[162:165], v[186:189], v[122:125]
	v_mfma_f32_16x16x32_bf16 v[118:121], v[166:169], v[182:185], v[118:121]
	v_mfma_f32_16x16x32_bf16 v[118:121], v[170:173], v[186:189], v[118:121]
	v_mfma_f32_16x16x32_bf16 v[106:109], v[158:161], v[190:193], v[106:109]
	v_mfma_f32_16x16x32_bf16 v[106:109], v[162:165], v[194:197], v[106:109]
	v_mfma_f32_16x16x32_bf16 v[102:105], v[166:169], v[190:193], v[102:105]
	v_mfma_f32_16x16x32_bf16 v[102:105], v[170:173], v[194:197], v[102:105]
	v_mfma_f32_16x16x32_bf16 v[90:93], v[158:161], v[198:201], v[90:93]
	v_mfma_f32_16x16x32_bf16 v[90:93], v[162:165], v[202:205], v[90:93]
	v_mfma_f32_16x16x32_bf16 v[86:89], v[166:169], v[198:201], v[86:89]
	v_mfma_f32_16x16x32_bf16 v[86:89], v[170:173], v[202:205], v[86:89]
	v_mfma_f32_16x16x32_bf16 v[74:77], v[158:161], v[206:209], v[74:77]
	v_mfma_f32_16x16x32_bf16 v[74:77], v[162:165], v[210:213], v[74:77]
	v_mfma_f32_16x16x32_bf16 v[70:73], v[166:169], v[206:209], v[70:73]
	v_mfma_f32_16x16x32_bf16 v[70:73], v[170:173], v[210:213], v[70:73]
	s_setprio 0
	s_barrier
	s_add_i32 s24, s48, s30
	v_lshl_add_u64 v[174:175], v[174:175], 0, s[92:93]
	s_mov_b32 m0, s24
	ds_read_b128 v[182:185], v251 offset:49152
	ds_read_b128 v[186:189], v251 offset:50176
	ds_read_b128 v[190:193], v251 offset:51200
	ds_read_b128 v[194:197], v251 offset:52224
	ds_read_b128 v[198:201], v251 offset:53248
	ds_read_b128 v[202:205], v251 offset:54272
	ds_read_b128 v[206:209], v251 offset:55296
	ds_read_b128 v[210:213], v251 offset:56320
	global_load_lds_dwordx4 v[174:175], off
	v_lshl_add_u64 v[174:175], v[214:215], 0, s[92:93]
	s_add_i32 m0, s24, 0x2000
	s_add_i32 s24, s49, s30
	global_load_lds_dwordx4 v[174:175], off
	v_lshl_add_u64 v[174:175], v[216:217], 0, s[92:93]
	s_mov_b32 m0, s24
	s_nop 0
	global_load_lds_dwordx4 v[174:175], off
	v_lshl_add_u64 v[174:175], v[218:219], 0, s[92:93]
	s_add_i32 m0, s24, 0x2000
	s_nop 0
	global_load_lds_dwordx4 v[174:175], off
	v_lshl_add_u64 v[174:175], v[220:221], 0, s[92:93]
	s_mov_b32 m0, s37
	s_nop 0
	global_load_lds_dwordx4 v[174:175], off
	v_lshl_add_u64 v[174:175], v[222:223], 0, s[92:93]
	s_mov_b32 m0, s38
	s_nop 0
	global_load_lds_dwordx4 v[174:175], off
	s_waitcnt vmcnt(8)
	s_waitcnt lgkmcnt(0)
	s_barrier
	s_setprio 1
	s_waitcnt lgkmcnt(0)
	v_mfma_f32_16x16x32_bf16 v[66:69], v[142:145], v[182:185], v[66:69]
	v_mfma_f32_16x16x32_bf16 v[66:69], v[146:149], v[186:189], v[66:69]
	v_mfma_f32_16x16x32_bf16 v[62:65], v[150:153], v[182:185], v[62:65]
	v_mfma_f32_16x16x32_bf16 v[62:65], v[154:157], v[186:189], v[62:65]
	v_mfma_f32_16x16x32_bf16 v[50:53], v[142:145], v[190:193], v[50:53]
	v_mfma_f32_16x16x32_bf16 v[50:53], v[146:149], v[194:197], v[50:53]
	v_mfma_f32_16x16x32_bf16 v[46:49], v[150:153], v[190:193], v[46:49]
	v_mfma_f32_16x16x32_bf16 v[46:49], v[154:157], v[194:197], v[46:49]
	v_mfma_f32_16x16x32_bf16 v[34:37], v[142:145], v[198:201], v[34:37]
	v_mfma_f32_16x16x32_bf16 v[34:37], v[146:149], v[202:205], v[34:37]
	v_mfma_f32_16x16x32_bf16 v[30:33], v[150:153], v[198:201], v[30:33]
	v_mfma_f32_16x16x32_bf16 v[30:33], v[154:157], v[202:205], v[30:33]
	v_mfma_f32_16x16x32_bf16 v[18:21], v[142:145], v[206:209], v[18:21]
	v_mfma_f32_16x16x32_bf16 v[18:21], v[146:149], v[210:213], v[18:21]
	v_mfma_f32_16x16x32_bf16 v[10:13], v[150:153], v[206:209], v[10:13]
	v_mfma_f32_16x16x32_bf16 v[10:13], v[154:157], v[210:213], v[10:13]
	s_setprio 0
	s_setprio 1
	v_mfma_f32_16x16x32_bf16 v[58:61], v[158:161], v[182:185], v[58:61]
	v_mfma_f32_16x16x32_bf16 v[58:61], v[162:165], v[186:189], v[58:61]
	v_mfma_f32_16x16x32_bf16 v[54:57], v[166:169], v[182:185], v[54:57]
	v_mfma_f32_16x16x32_bf16 v[54:57], v[170:173], v[186:189], v[54:57]
	v_mfma_f32_16x16x32_bf16 v[42:45], v[158:161], v[190:193], v[42:45]
	v_mfma_f32_16x16x32_bf16 v[42:45], v[162:165], v[194:197], v[42:45]
	v_mfma_f32_16x16x32_bf16 v[38:41], v[166:169], v[190:193], v[38:41]
	v_mfma_f32_16x16x32_bf16 v[38:41], v[170:173], v[194:197], v[38:41]
	v_mfma_f32_16x16x32_bf16 v[26:29], v[158:161], v[198:201], v[26:29]
	v_mfma_f32_16x16x32_bf16 v[26:29], v[162:165], v[202:205], v[26:29]
	v_mfma_f32_16x16x32_bf16 v[22:25], v[166:169], v[198:201], v[22:25]
	v_mfma_f32_16x16x32_bf16 v[22:25], v[170:173], v[202:205], v[22:25]
	v_mfma_f32_16x16x32_bf16 v[6:9], v[158:161], v[206:209], v[6:9]
	v_mfma_f32_16x16x32_bf16 v[6:9], v[162:165], v[210:213], v[6:9]
	v_mfma_f32_16x16x32_bf16 v[2:5], v[166:169], v[206:209], v[2:5]
	v_mfma_f32_16x16x32_bf16 v[2:5], v[170:173], v[210:213], v[2:5]
	s_setprio 0
	s_barrier
	s_add_u32 s22, s22, 0x100
	s_addc_u32 s23, s23, 0
	s_add_u32 s45, s45, 0x100
	s_addc_u32 s46, s46, 0
	s_cmp_ge_u32 s47, s39
	s_mov_b32 s24, s47
	s_cbranch_scc0 .LBB0_637
	s_nop 0
	s_nop 0
	s_nop 0
	s_nop 0
	s_nop 0
	s_nop 0
	s_nop 0
	s_nop 0
	s_nop 0
	s_nop 0
	s_nop 0
	s_nop 0
	s_nop 0
	s_nop 0
	s_nop 0
	s_nop 0
	s_nop 0
	s_nop 0
	s_nop 0
	s_nop 0
	s_nop 0
	s_nop 0
	s_nop 0
	s_nop 0
	s_nop 0
	s_nop 0
	s_nop 0
	s_nop 0
	s_nop 0
	s_nop 0
	s_nop 0
	s_nop 0
	s_nop 0
	s_nop 0
	s_nop 0
	s_nop 0
	s_nop 0
	s_nop 0
	s_nop 0
	s_nop 0
	s_nop 0
	s_nop 0
	s_nop 0
	s_nop 0
	s_nop 0
	s_nop 0
	s_nop 0
	s_nop 0
	s_nop 0
	s_nop 0
	s_nop 0
	s_nop 0
	s_nop 0
	s_nop 0
	s_nop 0
	s_nop 0
	s_nop 0
	s_nop 0
	s_nop 0
	s_nop 0
	s_nop 0
	s_and_b64 vcc, exec, s[18:19]
	s_cbranch_vccz .LBB0_640
	s_barrier
